# GDN scan chunk loads: incremental row addressing with scalar strides
# speedup vs baseline: 1.0047x; 1.0023x over previous
; __device__ __forceinline__ int TIDX() { int t = threadIdx.x; asm volatile("" : "+v"(t)); return t; }
; template <int TPW>
; __device__ __forceinline__ void gd_load(const P& p, int b, int h, int qc0, int vc, int dir, int g, int wv, GdRaw& R) {
;   int seq, T, c0; chunk_pos(g, seq, T, c0);
; #pragma unroll
;   for (int i = 0; i < TPW; ++i) {
;     int s = c0 + wv * TPW + i;
;     int t = dir ? T - 1 - s : s;
;     int rowg = tokrow(seq, b, t);
;     const u16* pq = p.nbuf + (unsigned)(rowg * D);
;     R.q0[i] = pq[qc0]; R.q1[i] = pq[qc0 + 64]; R.k0[i] = pq[512 + qc0]; R.k1[i] = pq[512 + qc0 + 64]; R.v[i] = pq[vc];
;     R.ab[i] = *reinterpret_cast<const float2*>(p.gab + (((size_t)dir * NT + rowg) * 4 + h) * 2);
;     R.kq[i] = p.kqa[(unsigned)(rowg * 8 + h)];
;   }
; }
; template <int NW>
; __device__ void scan_gdn(const P& p, int l, int b, int h, int dir, int part, LAS char* lds) {
;     ...
;   const int tid = TIDX(), lane = tid & 63, wv = (tid >> 6) & (NW - 1), tl = tid & (NTH - 1);
;   const int qc0 = h * 128 + lane;
;   const int vcol = h * 128 + part * NCOL;
;   const int vc = 1024 + vcol + (lane & (NCOL - 1));
;   u16* oo = osc_ptr(p, 1, dir);
;   f32x2 S2[8];
; #pragma unroll
;   for (int i = 0; i < 8; ++i) S2[i] = (f32x2){0.f, 0.f};
;   const int col = tl >> 3, dq = tl & 7;
.LBB0_209:
	s_and_b64 vcc, exec, s[0:1]
	s_cbranch_vccz .LBB0_282
	s_lshl_b32 s1, s64, 5
	v_mov_b32_e32 v18, v168
	s_lshl_b32 s0, s66, 7
	s_and_b32 s1, s1, 0x60
	s_or_b32 s1, s1, s0
	v_and_b32_e32 v19, 63, v18
	v_or_b32_e32 v2, s0, v19
	v_lshrrev_b32_e32 v0, 3, v18
	s_cmp_eq_u32 s59, 0
	s_movk_i32 s0, 0xff
	s_waitcnt vmcnt(0)
	v_and_b32_e32 v77, 24, v0
	s_cselect_b64 vcc, -1, 0
	s_cselect_b32 s99, 0, -1
	s_cselect_b32 s101, 0, -1
	s_xor_b32 s98, s99, 0x1000
	s_sub_i32 s98, s98, s99
	s_xor_b32 s100, s101, 32
	s_sub_i32 s100, s100, s101
	s_lshl_b32 s67, s62, 8
	v_bitop3_b32 v0, v0, s0, 24 bitop3:0x6c
	s_addk_i32 s67, 0x4000
	v_cndmask_b32_e32 v0, v0, v77, vcc
	v_or_b32_e32 v4, s67, v0
	v_lshlrev_b32_e32 v128, 11, v4
	v_lshl_add_u64 v[0:1], v[128:129], 1, s[92:93]
	v_lshlrev_b32_e32 v56, 1, v2
	v_mov_b32_e32 v57, v129
	v_lshl_add_u64 v[2:3], v[0:1], 0, v[56:57]
	v_ashrrev_i32_e32 v5, 31, v4
	v_lshl_or_b32 v128, v4, 3, s66
	global_load_ushort v68, v[2:3], off
	global_load_ushort v69, v[2:3], off offset:128
	global_load_ushort v70, v[2:3], off offset:1024
	global_load_ushort v71, v[2:3], off offset:1152
	v_lshl_add_u64 v[2:3], v[4:5], 0, s[28:29]
	v_lshl_add_u64 v[4:5], v[128:129], 2, s[18:19]
	global_load_dword v20, v[4:5], off
	v_or_b32_e32 v4, 1, v77
	v_xad_u32 v5, v77, -2, v183
	v_cndmask_b32_e32 v4, v5, v4, vcc
	v_and_or_b32 v76, v18, 31, s1
	v_readlane_b32 s0, v239, 26
	v_or_b32_e32 v6, s67, v4
	v_lshlrev_b64 v[2:3], 5, v[2:3]
	v_readlane_b32 s1, v239, 27
	v_readlane_b32 s2, v239, 28
	v_readlane_b32 s3, v239, 29
	v_lshlrev_b32_e32 v128, 11, v6
	s_lshl_b32 s0, s66, 3
	v_lshl_add_u64 v[2:3], s[2:3], 0, v[2:3]
	s_mov_b32 s1, s29
	v_lshl_add_u64 v[4:5], v[128:129], 1, s[92:93]
	v_lshlrev_b32_e32 v58, 1, v76
	v_mov_b32_e32 v59, v129
	v_lshl_add_u64 v[2:3], v[2:3], 0, s[0:1]
	v_lshl_add_u64 v[8:9], v[4:5], 0, v[56:57]
	v_lshl_add_u64 v[4:5], v[4:5], 0, v[58:59]
	v_ashrrev_i32_e32 v7, 31, v6
	v_lshl_or_b32 v128, v6, 3, s66
	global_load_dwordx2 v[2:3], v[2:3], off
	s_nop 0
	global_load_ushort v21, v[8:9], off
	global_load_ushort v22, v[8:9], off offset:128
	global_load_ushort v23, v[8:9], off offset:1024
	global_load_ushort v24, v[8:9], off offset:1152
	global_load_ushort v25, v[4:5], off offset:2048
	v_lshl_add_u64 v[4:5], v[6:7], 0, s[28:29]
	v_lshl_add_u64 v[6:7], v[128:129], 2, s[18:19]
	global_load_dword v26, v[6:7], off
	v_or_b32_e32 v6, 2, v77
	v_xad_u32 v7, v77, -3, v183
	v_cndmask_b32_e32 v6, v7, v6, vcc
	v_or_b32_e32 v8, s67, v6
	v_lshlrev_b64 v[4:5], 5, v[4:5]
	v_lshlrev_b32_e32 v128, 11, v8
	v_lshl_add_u64 v[4:5], s[2:3], 0, v[4:5]
	v_lshl_add_u64 v[6:7], v[128:129], 1, s[92:93]
	v_lshl_add_u64 v[4:5], v[4:5], 0, s[0:1]
	v_lshl_add_u64 v[10:11], v[6:7], 0, v[56:57]
	v_lshl_add_u64 v[6:7], v[6:7], 0, v[58:59]
	v_ashrrev_i32_e32 v9, 31, v8
	v_lshl_or_b32 v128, v8, 3, s66
	global_load_dwordx2 v[4:5], v[4:5], off
	s_nop 0
	global_load_ushort v27, v[10:11], off
	global_load_ushort v28, v[10:11], off offset:128
	global_load_ushort v29, v[10:11], off offset:1024
	global_load_ushort v30, v[10:11], off offset:1152
	global_load_ushort v31, v[6:7], off offset:2048
	v_lshl_add_u64 v[6:7], v[8:9], 0, s[28:29]
	v_lshl_add_u64 v[8:9], v[128:129], 2, s[18:19]
	global_load_dword v32, v[8:9], off
	v_or_b32_e32 v8, 3, v77
	v_xad_u32 v9, v77, -4, v183
	v_cndmask_b32_e32 v8, v9, v8, vcc
	v_or_b32_e32 v10, s67, v8
	v_lshlrev_b64 v[6:7], 5, v[6:7]
	v_lshlrev_b32_e32 v128, 11, v10
	v_lshl_add_u64 v[6:7], s[2:3], 0, v[6:7]
	v_lshl_add_u64 v[8:9], v[128:129], 1, s[92:93]
	v_lshl_add_u64 v[6:7], v[6:7], 0, s[0:1]
	v_lshl_add_u64 v[12:13], v[8:9], 0, v[56:57]
	v_lshl_add_u64 v[8:9], v[8:9], 0, v[58:59]
	v_ashrrev_i32_e32 v11, 31, v10
	v_lshl_or_b32 v128, v10, 3, s66
	global_load_dwordx2 v[6:7], v[6:7], off
	s_nop 0
	global_load_ushort v33, v[12:13], off
	global_load_ushort v34, v[12:13], off offset:128
	global_load_ushort v35, v[12:13], off offset:1024
	global_load_ushort v36, v[12:13], off offset:1152
	global_load_ushort v37, v[8:9], off offset:2048
	v_lshl_add_u64 v[8:9], v[10:11], 0, s[28:29]
	v_lshl_add_u64 v[10:11], v[128:129], 2, s[18:19]
	global_load_dword v38, v[10:11], off
	v_or_b32_e32 v10, 4, v77
	v_xad_u32 v11, v77, -5, v183
	v_cndmask_b32_e32 v10, v11, v10, vcc
	v_or_b32_e32 v12, s67, v10
	v_lshlrev_b64 v[8:9], 5, v[8:9]
	v_lshlrev_b32_e32 v128, 11, v12
; template <int TPW>
; __device__ __forceinline__ void gd_load(const P& p, int b, int h, int qc0, int vc, int dir, int g, int wv, GdRaw& R) {
;   int seq, T, c0; chunk_pos(g, seq, T, c0);
; #pragma unroll
;   for (int i = 0; i < TPW; ++i) {
;     int s = c0 + wv * TPW + i;
;     int t = dir ? T - 1 - s : s;
;     int rowg = tokrow(seq, b, t);
;     const u16* pq = p.nbuf + (unsigned)(rowg * D);
;     R.q0[i] = pq[qc0]; R.q1[i] = pq[qc0 + 64]; R.k0[i] = pq[512 + qc0]; R.k1[i] = pq[512 + qc0 + 64]; R.v[i] = pq[vc];
;     R.ab[i] = *reinterpret_cast<const float2*>(p.gab + (((size_t)dir * NT + rowg) * 4 + h) * 2);
;     R.kq[i] = p.kqa[(unsigned)(rowg * 8 + h)];
;   }
; }
	v_lshl_add_u64 v[8:9], s[2:3], 0, v[8:9]
	v_lshl_add_u64 v[10:11], v[128:129], 1, s[92:93]
	v_lshl_add_u64 v[8:9], v[8:9], 0, s[0:1]
	v_lshl_add_u64 v[14:15], v[10:11], 0, v[56:57]
	v_lshl_add_u64 v[10:11], v[10:11], 0, v[58:59]
	v_ashrrev_i32_e32 v13, 31, v12
	v_lshl_or_b32 v128, v12, 3, s66
	global_load_dwordx2 v[8:9], v[8:9], off
	s_nop 0
	global_load_ushort v39, v[14:15], off
	global_load_ushort v40, v[14:15], off offset:128
	global_load_ushort v41, v[14:15], off offset:1024
	global_load_ushort v42, v[14:15], off offset:1152
	global_load_ushort v43, v[10:11], off offset:2048
	v_lshl_add_u64 v[10:11], v[12:13], 0, s[28:29]
	v_lshl_add_u64 v[12:13], v[128:129], 2, s[18:19]
	global_load_dword v44, v[12:13], off
	v_or_b32_e32 v12, 5, v77
	v_xad_u32 v13, v77, -6, v183
	v_cndmask_b32_e32 v12, v13, v12, vcc
	v_or_b32_e32 v14, s67, v12
	v_lshlrev_b64 v[10:11], 5, v[10:11]
	v_lshlrev_b32_e32 v128, 11, v14
	v_lshl_add_u64 v[10:11], s[2:3], 0, v[10:11]
	v_lshl_add_u64 v[12:13], v[128:129], 1, s[92:93]
	v_lshl_add_u64 v[10:11], v[10:11], 0, s[0:1]
	v_lshl_add_u64 v[16:17], v[12:13], 0, v[56:57]
	v_lshl_add_u64 v[12:13], v[12:13], 0, v[58:59]
	v_ashrrev_i32_e32 v15, 31, v14
	v_lshl_or_b32 v128, v14, 3, s66
	global_load_dwordx2 v[10:11], v[10:11], off
	s_nop 0
	global_load_ushort v45, v[16:17], off
	global_load_ushort v46, v[16:17], off offset:128
	global_load_ushort v47, v[16:17], off offset:1024
	global_load_ushort v48, v[16:17], off offset:1152
	global_load_ushort v49, v[12:13], off offset:2048
	v_lshl_add_u64 v[12:13], v[14:15], 0, s[28:29]
	v_lshl_add_u64 v[14:15], v[128:129], 2, s[18:19]
	global_load_dword v50, v[14:15], off
	v_or_b32_e32 v14, 6, v77
	v_xad_u32 v15, v77, -7, v183
	v_cndmask_b32_e32 v14, v15, v14, vcc
	v_or_b32_e32 v16, s67, v14
	v_lshlrev_b64 v[12:13], 5, v[12:13]
	v_lshlrev_b32_e32 v128, 11, v16
	v_lshl_add_u64 v[12:13], s[2:3], 0, v[12:13]
	v_lshl_add_u64 v[14:15], v[128:129], 1, s[92:93]
	v_lshl_add_u64 v[12:13], v[12:13], 0, s[0:1]
	v_lshl_add_u64 v[54:55], v[14:15], 0, v[56:57]
	v_lshl_add_u64 v[14:15], v[14:15], 0, v[58:59]
	v_ashrrev_i32_e32 v17, 31, v16
	v_lshl_or_b32 v128, v16, 3, s66
	global_load_dwordx2 v[12:13], v[12:13], off
	s_nop 0
	global_load_ushort v51, v[54:55], off
	global_load_ushort v52, v[54:55], off offset:128
	global_load_ushort v53, v[54:55], off offset:1024
	s_nop 0
	global_load_ushort v54, v[54:55], off offset:1152
	v_cmp_gt_u32_e64 s[38:39], 32, v19
	global_load_ushort v55, v[14:15], off offset:2048
	v_lshl_add_u64 v[14:15], v[16:17], 0, s[28:29]
	v_lshl_add_u64 v[16:17], v[128:129], 2, s[18:19]
	global_load_dword v60, v[16:17], off
	v_or_b32_e32 v16, 7, v77
	v_xad_u32 v17, v77, -8, v183
	v_cndmask_b32_e32 v16, v17, v16, vcc
	v_or_b32_e32 v66, s67, v16
	v_lshlrev_b64 v[14:15], 5, v[14:15]
	v_lshlrev_b32_e32 v128, 11, v66
	v_lshl_add_u64 v[14:15], s[2:3], 0, v[14:15]
	v_lshl_add_u64 v[16:17], v[128:129], 1, s[92:93]
	v_lshl_add_u64 v[14:15], v[14:15], 0, s[0:1]
	v_lshl_add_u64 v[64:65], v[16:17], 0, v[56:57]
	v_lshl_add_u64 v[16:17], v[16:17], 0, v[58:59]
	v_ashrrev_i32_e32 v67, 31, v66
	global_load_dwordx2 v[14:15], v[14:15], off
	s_nop 0
	global_load_ushort v57, v[64:65], off
	global_load_ushort v61, v[64:65], off offset:128
	global_load_ushort v62, v[64:65], off offset:1024
	global_load_ushort v63, v[64:65], off offset:1152
	v_lshl_or_b32 v128, v66, 3, s66
	global_load_ushort v64, v[16:17], off offset:2048
	v_lshl_add_u64 v[16:17], v[66:67], 0, s[28:29]
	v_lshlrev_b64 v[16:17], 5, v[16:17]
	v_lshl_add_u64 v[16:17], s[2:3], 0, v[16:17]
	v_lshl_add_u64 v[16:17], v[16:17], 0, s[0:1]
	v_lshl_add_u64 v[66:67], v[128:129], 2, s[18:19]
	global_load_dwordx2 v[16:17], v[16:17], off
	s_nop 0
	global_load_dword v65, v[66:67], off
	v_lshlrev_b32_e32 v66, 2, v19
	s_waitcnt vmcnt(0)
	v_lshlrev_b32_e32 v67, 16, v68
	v_lshlrev_b32_e32 v68, 16, v69
	v_lshlrev_b32_e32 v69, 16, v70
	v_lshlrev_b32_e32 v70, 16, v71
	v_mul_u32_u24_e32 v71, 0x4d0, v77
	v_add3_u32 v78, 0, v66, v71
	ds_write2_b32 v78, v69, v70 offset1:68
	ds_write2_b32 v78, v67, v68 offset0:136 offset1:204
	s_and_saveexec_b64 s[0:1], s[38:39]
	s_cbranch_execz .LBB0_212
	v_lshl_add_u64 v[0:1], v[0:1], 0, v[58:59]
	global_load_ushort v0, v[0:1], off offset:2048
	s_waitcnt vmcnt(0)
	v_lshlrev_b32_e32 v0, 16, v0
	ds_write_b32 v78, v0 offset:1088

; template <int TPW>
; __device__ __forceinline__ void gd_load(const P& p, int b, int h, int qc0, int vc, int dir, int g, int wv, GdRaw& R) {
;   int seq, T, c0; chunk_pos(g, seq, T, c0);
; #pragma unroll
;   for (int i = 0; i < TPW; ++i) {
;     int s = c0 + wv * TPW + i;
;     int t = dir ? T - 1 - s : s;
;     int rowg = tokrow(seq, b, t);
;     const u16* pq = p.nbuf + (unsigned)(rowg * D);
;     R.q0[i] = pq[qc0]; R.q1[i] = pq[qc0 + 64]; R.k0[i] = pq[512 + qc0]; R.k1[i] = pq[512 + qc0 + 64]; R.v[i] = pq[vc];
;     R.ab[i] = *reinterpret_cast<const float2*>(p.gab + (((size_t)dir * NT + rowg) * 4 + h) * 2);
;     R.kq[i] = p.kqa[(unsigned)(rowg * 8 + h)];
;   }
; }
.LBB0_280:
	s_cmpk_gt_u32 s26, 0x85
	s_cbranch_scc1 .LBB0_243
	s_cmp_lt_u32 s26, 6
	s_cselect_b32 s20, 64, 0xffffff40
	s_cselect_b32 s22, 0x100, s96
	s_cselect_b32 s31, s67, s23
	s_add_i32 s20, s20, s27
	v_or_b32_e32 v6, s20, v77
	v_xad_u32 v0, v6, -1, s22
	v_cndmask_b32_e32 v0, v0, v6, vcc
	v_add_u32_e32 v0, s31, v0
	v_lshlrev_b32_e32 v128, 11, v0
	v_lshl_add_u64 v[2:3], v[128:129], 1, s[92:93]
	s_waitcnt vmcnt(6)
	v_mov_b32_e32 v57, v129
	s_waitcnt vmcnt(2)
	v_mov_b32_e32 v59, v129
	v_lshl_add_u64 v[4:5], v[2:3], 0, v[56:57]
	v_lshl_add_u64 v[2:3], v[2:3], 0, v[58:59]
	v_ashrrev_i32_e32 v1, 31, v0
	v_lshl_or_b32 v128, v0, 3, s66
	v_lshl_add_u64 v[246:247], v[0:1], 0, s[28:29]
	v_lshl_add_u64 v[244:245], v[128:129], 2, s[18:19]
	v_lshlrev_b64 v[246:247], 5, v[246:247]
	v_lshl_add_u64 v[246:247], s[2:3], 0, v[246:247]
	global_load_ushort v79, v[4:5], off
	global_load_ushort v80, v[4:5], off offset:128
	global_load_ushort v81, v[4:5], off offset:1024
	global_load_ushort v82, v[4:5], off offset:1152
	global_load_ushort v83, v[2:3], off offset:2048
	global_load_dword v84, v[244:245], off
	global_load_dwordx2 v[60:61], v[246:247], off
	v_lshl_add_u64 v[4:5], v[4:5], 0, s[98:99]
	v_lshl_add_u64 v[2:3], v[2:3], 0, s[98:99]
	v_lshl_add_u64 v[244:245], v[244:245], 0, s[100:101]
	v_lshl_add_u64 v[246:247], v[246:247], 0, s[100:101]
	global_load_ushort v85, v[4:5], off
	global_load_ushort v86, v[4:5], off offset:128
	global_load_ushort v87, v[4:5], off offset:1024
	global_load_ushort v88, v[4:5], off offset:1152
	global_load_ushort v89, v[2:3], off offset:2048
	global_load_dword v90, v[244:245], off
	global_load_dwordx2 v[62:63], v[246:247], off
	v_lshl_add_u64 v[4:5], v[4:5], 0, s[98:99]
	v_lshl_add_u64 v[2:3], v[2:3], 0, s[98:99]
	v_lshl_add_u64 v[244:245], v[244:245], 0, s[100:101]
	v_lshl_add_u64 v[246:247], v[246:247], 0, s[100:101]
	global_load_ushort v91, v[4:5], off
	global_load_ushort v92, v[4:5], off offset:128
	global_load_ushort v93, v[4:5], off offset:1024
	global_load_ushort v94, v[4:5], off offset:1152
	global_load_ushort v95, v[2:3], off offset:2048
	global_load_dword v96, v[244:245], off
	global_load_dwordx2 v[64:65], v[246:247], off
	v_lshl_add_u64 v[4:5], v[4:5], 0, s[98:99]
	v_lshl_add_u64 v[2:3], v[2:3], 0, s[98:99]
	v_lshl_add_u64 v[244:245], v[244:245], 0, s[100:101]
	v_lshl_add_u64 v[246:247], v[246:247], 0, s[100:101]
	global_load_ushort v103, v[4:5], off
	global_load_ushort v105, v[4:5], off offset:128
	global_load_ushort v107, v[4:5], off offset:1024
	global_load_ushort v108, v[4:5], off offset:1152
	global_load_ushort v111, v[2:3], off offset:2048
	global_load_dword v112, v[244:245], off
	global_load_dwordx2 v[66:67], v[246:247], off
	v_lshl_add_u64 v[4:5], v[4:5], 0, s[98:99]
	v_lshl_add_u64 v[2:3], v[2:3], 0, s[98:99]
	v_lshl_add_u64 v[244:245], v[244:245], 0, s[100:101]
	v_lshl_add_u64 v[246:247], v[246:247], 0, s[100:101]
	global_load_ushort v113, v[4:5], off
	global_load_ushort v114, v[4:5], off offset:128
	global_load_ushort v115, v[4:5], off offset:1024
	global_load_ushort v116, v[4:5], off offset:1152
	global_load_ushort v117, v[2:3], off offset:2048
	global_load_dword v118, v[244:245], off
	global_load_dwordx2 v[68:69], v[246:247], off
	v_lshl_add_u64 v[4:5], v[4:5], 0, s[98:99]
	v_lshl_add_u64 v[2:3], v[2:3], 0, s[98:99]
	v_lshl_add_u64 v[244:245], v[244:245], 0, s[100:101]
	v_lshl_add_u64 v[246:247], v[246:247], 0, s[100:101]
	global_load_ushort v119, v[4:5], off
	global_load_ushort v120, v[4:5], off offset:128
	global_load_ushort v121, v[4:5], off offset:1024
	global_load_ushort v122, v[4:5], off offset:1152
	global_load_ushort v123, v[2:3], off offset:2048
	global_load_dword v124, v[244:245], off
	global_load_dwordx2 v[70:71], v[246:247], off
	v_lshl_add_u64 v[4:5], v[4:5], 0, s[98:99]
	v_lshl_add_u64 v[2:3], v[2:3], 0, s[98:99]
	v_lshl_add_u64 v[244:245], v[244:245], 0, s[100:101]
	v_lshl_add_u64 v[246:247], v[246:247], 0, s[100:101]
	global_load_ushort v125, v[4:5], off
	global_load_ushort v126, v[4:5], off offset:128
	global_load_ushort v127, v[4:5], off offset:1024
	global_load_ushort v134, v[4:5], off offset:1152
	global_load_ushort v135, v[2:3], off offset:2048
	global_load_dword v136, v[244:245], off
	global_load_dwordx2 v[72:73], v[246:247], off
	v_lshl_add_u64 v[4:5], v[4:5], 0, s[98:99]
	v_lshl_add_u64 v[2:3], v[2:3], 0, s[98:99]
	v_lshl_add_u64 v[244:245], v[244:245], 0, s[100:101]
	v_lshl_add_u64 v[246:247], v[246:247], 0, s[100:101]
	global_load_ushort v57, v[4:5], off
	global_load_ushort v137, v[4:5], off offset:128
	global_load_ushort v138, v[4:5], off offset:1024
	global_load_ushort v139, v[4:5], off offset:1152
	global_load_ushort v59, v[2:3], off offset:2048
	global_load_dword v140, v[244:245], off
	global_load_dwordx2 v[74:75], v[246:247], off
	s_branch .LBB0_243

; #define LAS __attribute__((address_space(3)))
; __global__ void __launch_bounds__(NTHR, 2) mega(P p, int ph0, int ph1) {
;   extern __shared__ __attribute__((aligned(16))) char shm[];
;   volatile LAS unsigned* xst = (volatile LAS unsigned*)((LAS char*)shm + LDS_TOTAL - 16);
;   if (threadIdx.x < 4) xst[threadIdx.x] = 0u;
;   __syncthreads();
;   XcdBarrier xb = xcd_barrier_post(p.bar, xst);
;   for (int ph = ph0; ph < ph1; ++ph) {
;     int nrep = 1;
;     ...
;     if ((DUPMASK >> ph) & 1) nrep = 2;
;     ...
; #pragma unroll 1
;     for (int rep = 0; rep < nrep; ++rep) {
;       run_phase(p, ph, shm);
;       if (rep + 1 < nrep) xcd_barrier(xb);
;     }
;     if (ph + 1 < ph1) {
;       if (ph == ph0) cg::this_grid().sync(); else xcd_barrier(xb);
;     }
;     ...
;     if (ph == 5) { for (int q = 0; q < 20; ++q) xcd_barrier(xb); }
;     ...
;   }
; }
	.amdhsa_kernel _Z4mega1Pii
		.amdhsa_group_segment_fixed_size 0
		.amdhsa_private_segment_fixed_size 0
		.amdhsa_kernarg_size 664
		.amdhsa_user_sgpr_count 2
		.amdhsa_user_sgpr_dispatch_ptr 0
		.amdhsa_user_sgpr_queue_ptr 0
		.amdhsa_user_sgpr_kernarg_segment_ptr 1
		.amdhsa_user_sgpr_dispatch_id 0
		.amdhsa_user_sgpr_kernarg_preload_length 0
		.amdhsa_user_sgpr_kernarg_preload_offset 0
		.amdhsa_user_sgpr_private_segment_size 0
		.amdhsa_uses_dynamic_stack 0
		.amdhsa_enable_private_segment 0
		.amdhsa_system_sgpr_workgroup_id_x 1
		.amdhsa_system_sgpr_workgroup_id_y 0
		.amdhsa_system_sgpr_workgroup_id_z 0
		.amdhsa_system_sgpr_workgroup_info 0
		.amdhsa_system_vgpr_workitem_id 2
		.amdhsa_next_free_vgpr 256
		.amdhsa_next_free_sgpr 102
		.amdhsa_accum_offset 256
		.amdhsa_reserve_vcc 1
		.amdhsa_float_round_mode_32 0
		.amdhsa_float_round_mode_16_64 0
		.amdhsa_float_denorm_mode_32 3
		.amdhsa_float_denorm_mode_16_64 3
		.amdhsa_dx10_clamp 1
		.amdhsa_ieee_mode 1
		.amdhsa_fp16_overflow 0
		.amdhsa_tg_split 0
		.amdhsa_exception_fp_ieee_invalid_op 0
		.amdhsa_exception_fp_denorm_src 0
		.amdhsa_exception_fp_ieee_div_zero 0
		.amdhsa_exception_fp_ieee_overflow 0
		.amdhsa_exception_fp_ieee_underflow 0
		.amdhsa_exception_fp_ieee_inexact 0
		.amdhsa_exception_int_div_zero 0
	.end_amdhsa_kernel

; #define LAS __attribute__((address_space(3)))
; __global__ void __launch_bounds__(NTHR, 2) mega(P p, int ph0, int ph1) {
;   extern __shared__ __attribute__((aligned(16))) char shm[];
;   volatile LAS unsigned* xst = (volatile LAS unsigned*)((LAS char*)shm + LDS_TOTAL - 16);
;   if (threadIdx.x < 4) xst[threadIdx.x] = 0u;
;   __syncthreads();
;   XcdBarrier xb = xcd_barrier_post(p.bar, xst);
;   for (int ph = ph0; ph < ph1; ++ph) {
;     int nrep = 1;
;     ...
;     if ((DUPMASK >> ph) & 1) nrep = 2;
;     ...
; #pragma unroll 1
;     for (int rep = 0; rep < nrep; ++rep) {
;       run_phase(p, ph, shm);
;       if (rep + 1 < nrep) xcd_barrier(xb);
;     }
;     if (ph + 1 < ph1) {
;       if (ph == ph0) cg::this_grid().sync(); else xcd_barrier(xb);
;     }
;     ...
;     if (ph == 5) { for (int q = 0; q < 20; ++q) xcd_barrier(xb); }
;     ...
;   }
; }
amdhsa.kernels:
  - .agpr_count:     0
    .args:
      - .offset:         0
        .size:           400
        .value_kind:     by_value
      - .offset:         400
        .size:           4
        .value_kind:     by_value
      - .offset:         404
        .size:           4
        .value_kind:     by_value
      - .offset:         408
        .size:           4
        .value_kind:     hidden_block_count_x
      - .offset:         412
        .size:           4
        .value_kind:     hidden_block_count_y
      - .offset:         416
        .size:           4
        .value_kind:     hidden_block_count_z
      - .offset:         420
        .size:           2
        .value_kind:     hidden_group_size_x
      - .offset:         422
        .size:           2
        .value_kind:     hidden_group_size_y
      - .offset:         424
        .size:           2
        .value_kind:     hidden_group_size_z
      - .offset:         426
        .size:           2
        .value_kind:     hidden_remainder_x
      - .offset:         428
        .size:           2
        .value_kind:     hidden_remainder_y
      - .offset:         430
        .size:           2
        .value_kind:     hidden_remainder_z
      - .offset:         448
        .size:           8
        .value_kind:     hidden_global_offset_x
      - .offset:         456
        .size:           8
        .value_kind:     hidden_global_offset_y
      - .offset:         464
        .size:           8
        .value_kind:     hidden_global_offset_z
      - .offset:         472
        .size:           2
        .value_kind:     hidden_grid_dims
      - .offset:         496
        .size:           8
        .value_kind:     hidden_multigrid_sync_arg
      - .offset:         528
        .size:           4
        .value_kind:     hidden_dynamic_lds_size
    .group_segment_fixed_size: 0
    .kernarg_segment_align: 8
    .kernarg_segment_size: 664
    .language:       OpenCL C
    .language_version:
      - 2
      - 0
    .max_flat_workgroup_size: 512
    .name:           _Z4mega1Pii
    .private_segment_fixed_size: 0
    .sgpr_count:     108
    .sgpr_spill_count: 189
    .symbol:         _Z4mega1Pii.kd
    .uniform_work_group_size: 1
    .uses_dynamic_stack: false
    .vgpr_count:     256
    .vgpr_spill_count: 0
    .wavefront_size: 64
